# ResidH epilogue: non-returning ssq atomics, end-of-epilogue vmcnt(0) drain removed, relaxed first-iteration waits for non-first units
# baseline (speedup 1.0000x reference)
.Lc0r_first2:
	s_add_i32 s81, s64, 0x80
	s_and_b64 s[10:11], s[10:11], exec
	s_cselect_b32 s84, s24, s81
	s_cselect_b32 s85, s25, s65
	s_add_i32 s10, 0, 0x10000
	v_add_u32_e32 v3, s10, v208
	v_add_u32_e32 v144, s10, v209
	s_add_i32 s10, 0, 0x14000
	ds_read_b128 v[116:119], v3
	ds_read_b128 v[120:123], v3 offset:2048
	ds_read_b128 v[140:143], v144
	ds_read_b128 v[144:147], v144 offset:2048
	v_add_u32_e32 v3, s10, v208
	v_add_u32_e32 v176, s10, v209
	ds_read_b128 v[164:167], v3
	ds_read_b128 v[168:171], v3 offset:2048
	ds_read_b128 v[172:175], v176
	ds_read_b128 v[176:179], v176 offset:2048
	s_add_i32 s81, s84, 0x80
	s_add_i32 s82, s85, 0x80
	s_add_i32 s10, s29, s64
	s_mov_b32 m0, s53
	ds_read_b128 v[180:183], v214
	ds_read_b128 v[184:187], v214 offset:2048
	ds_read_b128 v[188:191], v215
	ds_read_b128 v[192:195], v215 offset:2048
	ds_read_b128 v[196:199], v214 offset:4096
	ds_read_b128 v[216:219], v214 offset:6144
	ds_read_b128 v[220:223], v215 offset:4096
	ds_read_b128 v[224:227], v215 offset:6144
	buffer_load_dwordx4 v204, s[48:51], s10 offen lds
	s_mov_b32 m0, s54
	s_nop 0
	buffer_load_dwordx4 v206, s[48:51], s10 offen lds
	s_waitcnt vmcnt(32)
	s_waitcnt lgkmcnt(0)
	s_barrier
	s_waitcnt lgkmcnt(0)
	v_mfma_f32_16x16x32_bf16 v[160:163], v[116:119], v[180:183], 0
	v_mfma_f32_16x16x32_bf16 v[152:155], v[120:123], v[180:183], 0
	v_mfma_f32_16x16x32_bf16 v[132:135], v[116:119], v[184:187], 0
	v_mfma_f32_16x16x32_bf16 v[124:127], v[120:123], v[184:187], 0
	v_mfma_f32_16x16x32_bf16 v[108:111], v[116:119], v[196:199], 0
	v_mfma_f32_16x16x32_bf16 v[100:103], v[120:123], v[196:199], 0
	v_mfma_f32_16x16x32_bf16 v[92:95], v[116:119], v[216:219], 0
	v_mfma_f32_16x16x32_bf16 v[84:87], v[120:123], v[216:219], 0
	v_mfma_f32_16x16x32_bf16 v[160:163], v[140:143], v[188:191], v[160:163]
	v_mfma_f32_16x16x32_bf16 v[152:155], v[144:147], v[188:191], v[152:155]
	v_mfma_f32_16x16x32_bf16 v[132:135], v[140:143], v[192:195], v[132:135]
	v_mfma_f32_16x16x32_bf16 v[124:127], v[144:147], v[192:195], v[124:127]
	v_mfma_f32_16x16x32_bf16 v[108:111], v[140:143], v[220:223], v[108:111]
	v_mfma_f32_16x16x32_bf16 v[100:103], v[144:147], v[220:223], v[100:103]
	v_mfma_f32_16x16x32_bf16 v[92:95], v[140:143], v[224:227], v[92:95]
	v_mfma_f32_16x16x32_bf16 v[84:87], v[144:147], v[224:227], v[84:87]
	v_mfma_f32_16x16x32_bf16 v[156:159], v[164:167], v[180:183], 0
	v_mfma_f32_16x16x32_bf16 v[148:151], v[168:171], v[180:183], 0
	v_mfma_f32_16x16x32_bf16 v[136:139], v[164:167], v[184:187], 0
	v_mfma_f32_16x16x32_bf16 v[128:131], v[168:171], v[184:187], 0
	v_mfma_f32_16x16x32_bf16 v[112:115], v[164:167], v[196:199], 0
	v_mfma_f32_16x16x32_bf16 v[104:107], v[168:171], v[196:199], 0
	v_mfma_f32_16x16x32_bf16 v[96:99], v[164:167], v[216:219], 0
	v_mfma_f32_16x16x32_bf16 v[88:91], v[168:171], v[216:219], 0
	v_mfma_f32_16x16x32_bf16 v[156:159], v[172:175], v[188:191], v[156:159]
	v_mfma_f32_16x16x32_bf16 v[148:151], v[176:179], v[188:191], v[148:151]
	v_mfma_f32_16x16x32_bf16 v[136:139], v[172:175], v[192:195], v[136:139]
	v_mfma_f32_16x16x32_bf16 v[128:131], v[176:179], v[192:195], v[128:131]
	v_mfma_f32_16x16x32_bf16 v[112:115], v[172:175], v[220:223], v[112:115]
	v_mfma_f32_16x16x32_bf16 v[104:107], v[176:179], v[220:223], v[104:107]
	v_mfma_f32_16x16x32_bf16 v[96:99], v[172:175], v[224:227], v[96:99]
	v_mfma_f32_16x16x32_bf16 v[88:91], v[176:179], v[224:227], v[88:91]
	s_barrier
	s_mov_b32 m0, s34
	s_mov_b32 s10, s50
	s_mov_b32 s11, s51
	ds_read_b128 v[180:183], v214 offset:16384
	ds_read_b128 v[184:187], v214 offset:18432
	ds_read_b128 v[188:191], v215 offset:16384
	ds_read_b128 v[192:195], v215 offset:18432
	ds_read_b128 v[196:199], v214 offset:20480
	ds_read_b128 v[216:219], v214 offset:22528
	ds_read_b128 v[220:223], v215 offset:20480
	ds_read_b128 v[224:227], v215 offset:22528
	buffer_load_dwordx4 v205, s[8:11], s85 offen lds
	s_mov_b32 m0, s35
	s_nop 0
	buffer_load_dwordx4 v207, s[8:11], s85 offen lds
	s_add_i32 s85, s85, s29
	s_mov_b32 m0, s36
	s_nop 0
	buffer_load_dwordx4 v205, s[8:11], s85 offen lds
	s_mov_b32 m0, s37
	s_nop 0
	buffer_load_dwordx4 v207, s[8:11], s85 offen lds
	s_mov_b32 m0, s31
	s_nop 0
	buffer_load_dwordx4 v204, s[48:51], s84 offen lds
	s_mov_b32 m0, s38
	s_nop 0
	buffer_load_dwordx4 v206, s[48:51], s84 offen lds
	s_waitcnt vmcnt(32)
	s_waitcnt lgkmcnt(0)
	s_barrier
	s_waitcnt lgkmcnt(0)
	v_mfma_f32_16x16x32_bf16 v[76:79], v[116:119], v[180:183], 0
	v_mfma_f32_16x16x32_bf16 v[68:71], v[120:123], v[180:183], 0
	v_mfma_f32_16x16x32_bf16 v[60:63], v[116:119], v[184:187], 0
	v_mfma_f32_16x16x32_bf16 v[52:55], v[120:123], v[184:187], 0
	v_mfma_f32_16x16x32_bf16 v[44:47], v[116:119], v[196:199], 0
	v_mfma_f32_16x16x32_bf16 v[36:39], v[120:123], v[196:199], 0
	v_mfma_f32_16x16x32_bf16 v[24:27], v[116:119], v[216:219], 0
	v_mfma_f32_16x16x32_bf16 v[20:23], v[120:123], v[216:219], 0
	v_mfma_f32_16x16x32_bf16 v[76:79], v[140:143], v[188:191], v[76:79]
	v_mfma_f32_16x16x32_bf16 v[68:71], v[144:147], v[188:191], v[68:71]
	v_mfma_f32_16x16x32_bf16 v[60:63], v[140:143], v[192:195], v[60:63]
	v_mfma_f32_16x16x32_bf16 v[52:55], v[144:147], v[192:195], v[52:55]
	v_mfma_f32_16x16x32_bf16 v[44:47], v[140:143], v[220:223], v[44:47]
	v_mfma_f32_16x16x32_bf16 v[36:39], v[144:147], v[220:223], v[36:39]
	v_mfma_f32_16x16x32_bf16 v[24:27], v[140:143], v[224:227], v[24:27]
	v_mfma_f32_16x16x32_bf16 v[20:23], v[144:147], v[224:227], v[20:23]
	v_mfma_f32_16x16x32_bf16 v[80:83], v[164:167], v[180:183], 0
	v_mfma_f32_16x16x32_bf16 v[72:75], v[168:171], v[180:183], 0
	v_mfma_f32_16x16x32_bf16 v[64:67], v[164:167], v[184:187], 0
	v_mfma_f32_16x16x32_bf16 v[56:59], v[168:171], v[184:187], 0
	v_mfma_f32_16x16x32_bf16 v[48:51], v[164:167], v[196:199], 0
	v_mfma_f32_16x16x32_bf16 v[40:43], v[168:171], v[196:199], 0
	v_mfma_f32_16x16x32_bf16 v[28:31], v[164:167], v[216:219], 0
	v_mfma_f32_16x16x32_bf16 v[32:35], v[168:171], v[216:219], 0
	v_mfma_f32_16x16x32_bf16 v[80:83], v[172:175], v[188:191], v[80:83]
	v_mfma_f32_16x16x32_bf16 v[72:75], v[176:179], v[188:191], v[72:75]
	v_mfma_f32_16x16x32_bf16 v[64:67], v[172:175], v[192:195], v[64:67]
	v_mfma_f32_16x16x32_bf16 v[56:59], v[176:179], v[192:195], v[56:59]
	v_mfma_f32_16x16x32_bf16 v[48:51], v[172:175], v[220:223], v[48:51]
	v_mfma_f32_16x16x32_bf16 v[40:43], v[176:179], v[220:223], v[40:43]
	v_mfma_f32_16x16x32_bf16 v[28:31], v[172:175], v[224:227], v[28:31]
	v_mfma_f32_16x16x32_bf16 v[32:35], v[176:179], v[224:227], v[32:35]
	s_barrier
	s_add_i32 s85, 0, 0x18000
	v_add_u32_e32 v3, s85, v208
	v_add_u32_e32 v144, s85, v209
	s_add_i32 s85, 0, 0x1c000
	ds_read_b128 v[116:119], v3
	ds_read_b128 v[120:123], v3 offset:2048
	ds_read_b128 v[140:143], v144
	ds_read_b128 v[144:147], v144 offset:2048
	v_add_u32_e32 v3, s85, v208
	v_add_u32_e32 v176, s85, v209
	ds_read_b128 v[164:167], v3
	ds_read_b128 v[168:171], v3 offset:2048
	ds_read_b128 v[172:175], v176
	ds_read_b128 v[176:179], v176 offset:2048
	s_add_i32 s84, s84, s29
	s_mov_b32 m0, s39
	ds_read_b128 v[180:183], v214 offset:32768
	ds_read_b128 v[184:187], v214 offset:34816
	ds_read_b128 v[188:191], v215 offset:32768
	ds_read_b128 v[192:195], v215 offset:34816
	ds_read_b128 v[196:199], v214 offset:36864
	ds_read_b128 v[216:219], v214 offset:38912
	ds_read_b128 v[220:223], v215 offset:36864
	ds_read_b128 v[224:227], v215 offset:38912
	buffer_load_dwordx4 v204, s[48:51], s84 offen lds
	s_mov_b32 m0, s40
	s_nop 0
	buffer_load_dwordx4 v206, s[48:51], s84 offen lds
	s_waitcnt vmcnt(8)
	s_waitcnt lgkmcnt(0)
	s_barrier
	s_waitcnt lgkmcnt(0)
	v_mfma_f32_16x16x32_bf16 v[160:163], v[116:119], v[180:183], v[160:163]
	v_mfma_f32_16x16x32_bf16 v[152:155], v[120:123], v[180:183], v[152:155]
	v_mfma_f32_16x16x32_bf16 v[132:135], v[116:119], v[184:187], v[132:135]
	v_mfma_f32_16x16x32_bf16 v[124:127], v[120:123], v[184:187], v[124:127]
	v_mfma_f32_16x16x32_bf16 v[108:111], v[116:119], v[196:199], v[108:111]
	v_mfma_f32_16x16x32_bf16 v[100:103], v[120:123], v[196:199], v[100:103]
	v_mfma_f32_16x16x32_bf16 v[92:95], v[116:119], v[216:219], v[92:95]
	v_mfma_f32_16x16x32_bf16 v[84:87], v[120:123], v[216:219], v[84:87]
	v_mfma_f32_16x16x32_bf16 v[160:163], v[140:143], v[188:191], v[160:163]
	v_mfma_f32_16x16x32_bf16 v[152:155], v[144:147], v[188:191], v[152:155]
	v_mfma_f32_16x16x32_bf16 v[132:135], v[140:143], v[192:195], v[132:135]
	v_mfma_f32_16x16x32_bf16 v[124:127], v[144:147], v[192:195], v[124:127]
	v_mfma_f32_16x16x32_bf16 v[108:111], v[140:143], v[220:223], v[108:111]
	v_mfma_f32_16x16x32_bf16 v[100:103], v[144:147], v[220:223], v[100:103]
	v_mfma_f32_16x16x32_bf16 v[92:95], v[140:143], v[224:227], v[92:95]
	v_mfma_f32_16x16x32_bf16 v[84:87], v[144:147], v[224:227], v[84:87]
	v_mfma_f32_16x16x32_bf16 v[156:159], v[164:167], v[180:183], v[156:159]
	v_mfma_f32_16x16x32_bf16 v[148:151], v[168:171], v[180:183], v[148:151]
	v_mfma_f32_16x16x32_bf16 v[136:139], v[164:167], v[184:187], v[136:139]
	v_mfma_f32_16x16x32_bf16 v[128:131], v[168:171], v[184:187], v[128:131]
	v_mfma_f32_16x16x32_bf16 v[112:115], v[164:167], v[196:199], v[112:115]
	v_mfma_f32_16x16x32_bf16 v[104:107], v[168:171], v[196:199], v[104:107]
	v_mfma_f32_16x16x32_bf16 v[96:99], v[164:167], v[216:219], v[96:99]
	v_mfma_f32_16x16x32_bf16 v[88:91], v[168:171], v[216:219], v[88:91]
	v_mfma_f32_16x16x32_bf16 v[156:159], v[172:175], v[188:191], v[156:159]
	v_mfma_f32_16x16x32_bf16 v[148:151], v[176:179], v[188:191], v[148:151]
	v_mfma_f32_16x16x32_bf16 v[136:139], v[172:175], v[192:195], v[136:139]
	v_mfma_f32_16x16x32_bf16 v[128:131], v[176:179], v[192:195], v[128:131]
	v_mfma_f32_16x16x32_bf16 v[112:115], v[172:175], v[220:223], v[112:115]
	v_mfma_f32_16x16x32_bf16 v[104:107], v[176:179], v[220:223], v[104:107]
	v_mfma_f32_16x16x32_bf16 v[96:99], v[172:175], v[224:227], v[96:99]
	v_mfma_f32_16x16x32_bf16 v[88:91], v[176:179], v[224:227], v[88:91]
	s_barrier
	s_mov_b32 m0, s41
	ds_read_b128 v[180:183], v214 offset:49152
	ds_read_b128 v[184:187], v214 offset:51200
	ds_read_b128 v[188:191], v215 offset:49152
	ds_read_b128 v[192:195], v215 offset:51200
	ds_read_b128 v[196:199], v214 offset:53248
	ds_read_b128 v[216:219], v214 offset:55296
	ds_read_b128 v[220:223], v215 offset:53248
	ds_read_b128 v[224:227], v215 offset:55296
	buffer_load_dwordx4 v205, s[8:11], s82 offen lds
	s_mov_b32 m0, s42
	s_nop 0
	buffer_load_dwordx4 v207, s[8:11], s82 offen lds
	s_add_i32 s82, s82, s29
	s_mov_b32 m0, s45
	s_nop 0
	buffer_load_dwordx4 v205, s[8:11], s82 offen lds
	s_mov_b32 m0, s46
	s_nop 0
	buffer_load_dwordx4 v207, s[8:11], s82 offen lds
	s_mov_b32 m0, s43
	s_nop 0
	buffer_load_dwordx4 v204, s[48:51], s81 offen lds
	s_mov_b32 m0, s44
	s_nop 0
	buffer_load_dwordx4 v206, s[48:51], s81 offen lds
	s_waitcnt vmcnt(8)
	s_waitcnt lgkmcnt(0)
	s_barrier
	s_waitcnt lgkmcnt(0)
	v_mfma_f32_16x16x32_bf16 v[76:79], v[116:119], v[180:183], v[76:79]
	v_mfma_f32_16x16x32_bf16 v[68:71], v[120:123], v[180:183], v[68:71]
	v_mfma_f32_16x16x32_bf16 v[60:63], v[116:119], v[184:187], v[60:63]
	v_mfma_f32_16x16x32_bf16 v[52:55], v[120:123], v[184:187], v[52:55]
	v_mfma_f32_16x16x32_bf16 v[44:47], v[116:119], v[196:199], v[44:47]
	v_mfma_f32_16x16x32_bf16 v[36:39], v[120:123], v[196:199], v[36:39]
	v_mfma_f32_16x16x32_bf16 v[24:27], v[116:119], v[216:219], v[24:27]
	v_mfma_f32_16x16x32_bf16 v[20:23], v[120:123], v[216:219], v[20:23]
	v_mfma_f32_16x16x32_bf16 v[76:79], v[140:143], v[188:191], v[76:79]
	v_mfma_f32_16x16x32_bf16 v[68:71], v[144:147], v[188:191], v[68:71]
	v_mfma_f32_16x16x32_bf16 v[60:63], v[140:143], v[192:195], v[60:63]
	v_mfma_f32_16x16x32_bf16 v[52:55], v[144:147], v[192:195], v[52:55]
	v_mfma_f32_16x16x32_bf16 v[44:47], v[140:143], v[220:223], v[44:47]
	v_mfma_f32_16x16x32_bf16 v[36:39], v[144:147], v[220:223], v[36:39]
	v_mfma_f32_16x16x32_bf16 v[24:27], v[140:143], v[224:227], v[24:27]
	v_mfma_f32_16x16x32_bf16 v[20:23], v[144:147], v[224:227], v[20:23]
	v_mfma_f32_16x16x32_bf16 v[80:83], v[164:167], v[180:183], v[80:83]
	v_mfma_f32_16x16x32_bf16 v[72:75], v[168:171], v[180:183], v[72:75]
	v_mfma_f32_16x16x32_bf16 v[64:67], v[164:167], v[184:187], v[64:67]
	v_mfma_f32_16x16x32_bf16 v[56:59], v[168:171], v[184:187], v[56:59]
	v_mfma_f32_16x16x32_bf16 v[48:51], v[164:167], v[196:199], v[48:51]
	v_mfma_f32_16x16x32_bf16 v[40:43], v[168:171], v[196:199], v[40:43]
	v_mfma_f32_16x16x32_bf16 v[28:31], v[164:167], v[216:219], v[28:31]
	v_mfma_f32_16x16x32_bf16 v[32:35], v[168:171], v[216:219], v[32:35]
	v_mfma_f32_16x16x32_bf16 v[80:83], v[172:175], v[188:191], v[80:83]
	v_mfma_f32_16x16x32_bf16 v[72:75], v[176:179], v[188:191], v[72:75]
	v_mfma_f32_16x16x32_bf16 v[64:67], v[172:175], v[192:195], v[64:67]
	v_mfma_f32_16x16x32_bf16 v[56:59], v[176:179], v[192:195], v[56:59]
	v_mfma_f32_16x16x32_bf16 v[48:51], v[172:175], v[220:223], v[48:51]
	v_mfma_f32_16x16x32_bf16 v[40:43], v[176:179], v[220:223], v[40:43]
	v_mfma_f32_16x16x32_bf16 v[28:31], v[172:175], v[224:227], v[28:31]
	v_mfma_f32_16x16x32_bf16 v[32:35], v[176:179], v[224:227], v[32:35]
	s_barrier
	s_branch .Lc0r_tail

.LBB0_382:
	s_cmp_eq_u32 s78, 0
	s_cbranch_scc0 .Lc0r_nf
	s_cmp_eq_u32 s58, 1
	s_cbranch_scc1 .Lc0r_first
	s_branch .Lc0r_first2
.Lc0r_nf:
	s_cmp_eq_u32 s78, s52
	s_cbranch_scc0 .Lc0r_norm
	s_cmp_eq_u64 s[4:5], 0
	s_cbranch_scc1 .Lc0r_final

.LBB0_387:
	s_mov_b64 s[10:11], s[16:17]
	s_waitcnt vmcnt(16)
	v_lshl_add_u32 v196, s22, 8, v211
	s_add_u32 s22, s10, 0x20000
	v_lshl_or_b32 v2, s23, 8, v212
	s_addc_u32 s23, s11, 0
	s_add_u32 s10, s10, 0x30000
	s_addc_u32 s11, s11, 0
	v_lshl_add_u32 v0, v196, 12, v0
	global_load_dwordx4 v[192:195], v0, s[22:23]
	global_load_dwordx4 v[188:191], v0, s[22:23] offset:256
	global_load_dwordx4 v[184:187], v0, s[10:11]
	global_load_dwordx4 v[180:183], v0, s[10:11] offset:256
	s_mov_b64 s[10:11], s[16:17]
	s_add_u32 s22, s10, 0x80000
	s_addc_u32 s23, s11, 0
	s_add_u32 s10, s10, 0x90000
	s_addc_u32 s11, s11, 0
	global_load_dwordx4 v[176:179], v0, s[22:23]
	global_load_dwordx4 v[172:175], v0, s[22:23] offset:256
	global_load_dwordx4 v[168:171], v0, s[10:11]
	global_load_dwordx4 v[164:167], v0, s[10:11] offset:256
	s_mov_b64 s[10:11], s[16:17]
	s_add_u32 s22, s10, 0xa0000
	v_cvt_f32_f16_e32 v218, v4
	v_cvt_f32_f16_sdwa v219, v4 dst_sel:DWORD dst_unused:UNUSED_PAD src0_sel:WORD_1
	s_addc_u32 s23, s11, 0
	v_cvt_f32_f16_e32 v216, v5
	v_cvt_f32_f16_sdwa v217, v5 dst_sel:DWORD dst_unused:UNUSED_PAD src0_sel:WORD_1
	s_add_u32 s10, s10, 0xb0000
	global_load_dwordx4 v[144:147], v0, s[22:23]
	global_load_dwordx4 v[140:143], v0, s[22:23] offset:256
	s_addc_u32 s11, s11, 0
	global_load_dwordx4 v[120:123], v0, s[10:11]
	global_load_dwordx4 v[116:119], v0, s[10:11] offset:256
	s_mov_b32 s10, s27
	s_mov_b64 s[22:23], s[18:19]
	s_mov_b64 s[24:25], s[16:17]
	v_ashrrev_i32_e32 v3, 31, v2
	v_pk_fma_f32 v[160:161], v[160:161], s[10:11], v[218:219] op_sel_hi:[1,0,1]
	v_cvt_f32_f16_e32 v218, v6
	v_cvt_f32_f16_sdwa v219, v6 dst_sel:DWORD dst_unused:UNUSED_PAD src0_sel:WORD_1
	v_pk_fma_f32 v[162:163], v[162:163], s[10:11], v[216:217] op_sel_hi:[1,0,1]
	v_cvt_f32_f16_e32 v216, v7
	v_cvt_f32_f16_sdwa v217, v7 dst_sel:DWORD dst_unused:UNUSED_PAD src0_sel:WORD_1
	v_pk_fma_f32 v[218:219], v[152:153], s[10:11], v[218:219] op_sel_hi:[1,0,1]
	v_cvt_pk_f16_f32 v153, v162, v163
	v_cvt_pk_f16_f32 v152, v160, v161
	v_pk_fma_f32 v[154:155], v[154:155], s[10:11], v[216:217] op_sel_hi:[1,0,1]
	v_cvt_f32_f16_sdwa v0, v153 dst_sel:DWORD dst_unused:UNUSED_PAD src0_sel:WORD_1
	v_cvt_f32_f16_sdwa v160, v152 dst_sel:DWORD dst_unused:UNUSED_PAD src0_sel:WORD_1
	v_cvt_pk_f16_f32 v155, v154, v155
	v_cvt_pk_f16_f32 v154, v218, v219
	v_ashrrev_i32_e32 v197, 31, v196
	v_cvt_f32_f16_sdwa v161, v155 dst_sel:DWORD dst_unused:UNUSED_PAD src0_sel:WORD_1
	v_cvt_f32_f16_sdwa v162, v154 dst_sel:DWORD dst_unused:UNUSED_PAD src0_sel:WORD_1
	v_lshl_add_u64 v[198:199], v[2:3], 1, s[24:25]
	v_lshlrev_b64 v[2:3], 12, v[196:197]
	v_lshl_add_u64 v[2:3], v[198:199], 0, v[2:3]
	v_mul_f32_e32 v160, v160, v160
	v_mul_f32_e32 v0, v0, v0
	global_store_dwordx4 v[2:3], v[152:155], off
	v_fma_mix_f32 v0, v153, v153, v0 op_sel_hi:[1,1,0]
	s_nop 0
	v_fma_mix_f32 v152, v152, v152, v160 op_sel_hi:[1,1,0]
	v_mul_f32_e32 v153, v161, v161
	v_add_f32_e32 v0, v152, v0
	v_mul_f32_e32 v152, v162, v162
	v_fma_mix_f32 v152, v154, v154, v152 op_sel_hi:[1,1,0]
	v_fma_mix_f32 v153, v155, v155, v153 op_sel_hi:[1,1,0]
	v_cvt_f32_f16_e32 v154, v8
	v_add_f32_e32 v152, v152, v153
	v_add_f32_e32 v0, v0, v152
	v_cvt_f32_f16_e32 v152, v9
	v_cvt_f32_f16_sdwa v153, v9 dst_sel:DWORD dst_unused:UNUSED_PAD src0_sel:WORD_1
	v_cvt_f32_f16_sdwa v155, v8 dst_sel:DWORD dst_unused:UNUSED_PAD src0_sel:WORD_1
	v_pk_fma_f32 v[152:153], v[158:159], s[10:11], v[152:153] op_sel_hi:[1,0,1]
	v_cvt_f32_f16_e32 v158, v10
	v_cvt_f32_f16_sdwa v159, v10 dst_sel:DWORD dst_unused:UNUSED_PAD src0_sel:WORD_1
	v_pk_fma_f32 v[154:155], v[156:157], s[10:11], v[154:155] op_sel_hi:[1,0,1]
	v_cvt_f32_f16_e32 v156, v11
	v_cvt_f32_f16_sdwa v157, v11 dst_sel:DWORD dst_unused:UNUSED_PAD src0_sel:WORD_1
	v_pk_fma_f32 v[158:159], v[148:149], s[10:11], v[158:159] op_sel_hi:[1,0,1]
	v_cvt_pk_f16_f32 v149, v152, v153
	v_cvt_pk_f16_f32 v148, v154, v155
	v_pk_fma_f32 v[150:151], v[150:151], s[10:11], v[156:157] op_sel_hi:[1,0,1]
	v_cvt_f32_f16_sdwa v152, v149 dst_sel:DWORD dst_unused:UNUSED_PAD src0_sel:WORD_1
	v_cvt_f32_f16_sdwa v153, v148 dst_sel:DWORD dst_unused:UNUSED_PAD src0_sel:WORD_1
	v_cvt_pk_f16_f32 v151, v150, v151
	v_cvt_pk_f16_f32 v150, v158, v159
	v_cvt_f32_f16_sdwa v155, v150 dst_sel:DWORD dst_unused:UNUSED_PAD src0_sel:WORD_1
	v_cvt_f32_f16_sdwa v154, v151 dst_sel:DWORD dst_unused:UNUSED_PAD src0_sel:WORD_1
	v_mul_f32_e32 v153, v153, v153
	v_mul_f32_e32 v152, v152, v152
	global_store_dwordx4 v[2:3], v[148:151], off offset:256
	s_nop 1
	v_fma_mix_f32 v148, v148, v148, v153 op_sel_hi:[1,1,0]
	v_fma_mix_f32 v149, v149, v149, v152 op_sel_hi:[1,1,0]
	v_mov_b64_e32 v[152:153], 0
	v_add_f32_e32 v148, v148, v149
	v_mul_f32_e32 v149, v155, v155
	v_fma_mix_f32 v149, v150, v150, v149 op_sel_hi:[1,1,0]
	v_mul_f32_e32 v150, v154, v154
	v_fma_mix_f32 v150, v151, v151, v150 op_sel_hi:[1,1,0]
	s_nop 0
	v_add_f32_e32 v149, v149, v150
	v_add_f32_e32 v148, v148, v149
	v_add_f32_e32 v0, v0, v148
	v_mbcnt_lo_u32_b32 v148, -1, 0
	v_mbcnt_hi_u32_b32 v148, -1, v148
	v_mov_b64_e32 v[150:151], 0
	v_lshlrev_b32_e32 v148, 2, v148
	v_xor_b32_e32 v149, 64, v148
	ds_bpermute_b32 v149, v149, v0
	v_xor_b32_e32 v148, 0x80, v148
	s_waitcnt lgkmcnt(0)
	v_add_f32_e32 v0, v0, v149
	ds_bpermute_b32 v154, v148, v0
	v_lshl_add_u64 v[148:149], v[196:197], 3, s[22:23]
	s_and_saveexec_b64 s[22:23], s[6:7]
	s_cbranch_execz .LBB0_389
	s_waitcnt lgkmcnt(0)
	v_add_f32_e32 v152, v0, v154
	v_cvt_i32_f32_e32 v0, v152
	v_cvt_f32_i32_e32 v153, v0
	v_lshlrev_b64 v[154:155], 24, v[0:1]
	v_sub_f32_e32 v152, v152, v153
	v_mul_f32_e32 v152, 0x4b800000, v152
	v_cvt_i32_f32_e32 v152, v152
	v_mov_b32_e32 v153, v1
	v_lshl_add_u64 v[152:153], v[154:155], 0, v[152:153]
	global_atomic_add_x2 v[148:149], v[152:153], off
.LBB0_389:
	s_or_b64 exec, exec, s[22:23]
	v_cvt_f32_f16_sdwa v157, v12 dst_sel:DWORD dst_unused:UNUSED_PAD src0_sel:WORD_1
	v_cvt_f32_f16_e32 v156, v12
	v_cvt_f32_f16_sdwa v159, v13 dst_sel:DWORD dst_unused:UNUSED_PAD src0_sel:WORD_1
	v_cvt_f32_f16_e32 v158, v13
	s_mov_b32 s11, s10
	s_mov_b32 s22, s10
	s_mov_b32 s23, s10
	v_pk_fma_f32 v[132:133], v[132:133], s[10:11], v[156:157]
	v_cvt_f32_f16_sdwa v157, v14 dst_sel:DWORD dst_unused:UNUSED_PAD src0_sel:WORD_1
	v_cvt_f32_f16_e32 v156, v14
	v_pk_fma_f32 v[134:135], v[134:135], s[22:23], v[158:159]
	v_cvt_f32_f16_sdwa v159, v15 dst_sel:DWORD dst_unused:UNUSED_PAD src0_sel:WORD_1
	v_cvt_f32_f16_e32 v158, v15
	v_pk_fma_f32 v[156:157], v[124:125], s[10:11], v[156:157]
	v_cvt_pk_f16_f32 v125, v134, v135
	v_cvt_pk_f16_f32 v124, v132, v133
	v_pk_fma_f32 v[126:127], v[126:127], s[22:23], v[158:159]
	v_cvt_f32_f16_sdwa v0, v125 dst_sel:DWORD dst_unused:UNUSED_PAD src0_sel:WORD_1
	v_cvt_f32_f16_sdwa v132, v124 dst_sel:DWORD dst_unused:UNUSED_PAD src0_sel:WORD_1
	s_waitcnt lgkmcnt(0)
	v_or_b32_e32 v154, 16, v196
	v_cvt_pk_f16_f32 v127, v126, v127
	v_cvt_pk_f16_f32 v126, v156, v157
	v_ashrrev_i32_e32 v155, 31, v154
	v_cvt_f32_f16_sdwa v133, v127 dst_sel:DWORD dst_unused:UNUSED_PAD src0_sel:WORD_1
	v_cvt_f32_f16_sdwa v134, v126 dst_sel:DWORD dst_unused:UNUSED_PAD src0_sel:WORD_1
	v_lshlrev_b64 v[154:155], 12, v[154:155]
	v_lshl_add_u64 v[154:155], v[198:199], 0, v[154:155]
	v_mul_f32_e32 v132, v132, v132
	v_mul_f32_e32 v0, v0, v0
	global_store_dwordx4 v[154:155], v[124:127], off
	v_fma_mix_f32 v0, v125, v125, v0 op_sel_hi:[1,1,0]
	v_cvt_f32_f16_sdwa v135, v19 dst_sel:DWORD dst_unused:UNUSED_PAD src0_sel:WORD_1
	v_fma_mix_f32 v124, v124, v124, v132 op_sel_hi:[1,1,0]
	v_mul_f32_e32 v125, v133, v133
	v_add_f32_e32 v0, v124, v0
	v_mul_f32_e32 v124, v134, v134
	v_fma_mix_f32 v124, v126, v126, v124 op_sel_hi:[1,1,0]
	v_fma_mix_f32 v125, v127, v127, v125 op_sel_hi:[1,1,0]
	v_cvt_f32_f16_sdwa v127, v17 dst_sel:DWORD dst_unused:UNUSED_PAD src0_sel:WORD_1
	v_add_f32_e32 v124, v124, v125
	v_add_f32_e32 v0, v0, v124
	v_cvt_f32_f16_sdwa v125, v16 dst_sel:DWORD dst_unused:UNUSED_PAD src0_sel:WORD_1
	v_cvt_f32_f16_e32 v124, v16
	v_cvt_f32_f16_e32 v126, v17
	v_cvt_f32_f16_e32 v134, v19
	v_pk_fma_f32 v[132:133], v[136:137], s[10:11], v[124:125]
	v_cvt_f32_f16_sdwa v125, v18 dst_sel:DWORD dst_unused:UNUSED_PAD src0_sel:WORD_1
	v_cvt_f32_f16_e32 v124, v18
	v_pk_fma_f32 v[126:127], v[138:139], s[22:23], v[126:127]
	v_pk_fma_f32 v[130:131], v[130:131], s[22:23], v[134:135]
	v_pk_fma_f32 v[128:129], v[128:129], s[10:11], v[124:125]
	v_cvt_pk_f16_f32 v125, v126, v127
	v_cvt_pk_f16_f32 v124, v132, v133
	v_cvt_pk_f16_f32 v126, v128, v129
	v_cvt_f32_f16_sdwa v128, v125 dst_sel:DWORD dst_unused:UNUSED_PAD src0_sel:WORD_1
	v_cvt_f32_f16_sdwa v129, v124 dst_sel:DWORD dst_unused:UNUSED_PAD src0_sel:WORD_1
	v_cvt_pk_f16_f32 v127, v130, v131
	v_cvt_f32_f16_sdwa v131, v126 dst_sel:DWORD dst_unused:UNUSED_PAD src0_sel:WORD_1
	v_cvt_f32_f16_sdwa v130, v127 dst_sel:DWORD dst_unused:UNUSED_PAD src0_sel:WORD_1
	v_mul_f32_e32 v129, v129, v129
	v_mul_f32_e32 v128, v128, v128
	global_store_dwordx4 v[154:155], v[124:127], off offset:256
	s_nop 1
	v_fma_mix_f32 v124, v124, v124, v129 op_sel_hi:[1,1,0]
	v_fma_mix_f32 v125, v125, v125, v128 op_sel_hi:[1,1,0]
	s_nop 0
	v_add_f32_e32 v124, v124, v125
	v_mul_f32_e32 v125, v131, v131
	v_fma_mix_f32 v125, v126, v126, v125 op_sel_hi:[1,1,0]
	v_mul_f32_e32 v126, v130, v130
	v_fma_mix_f32 v126, v127, v127, v126 op_sel_hi:[1,1,0]
	s_nop 0
	v_add_f32_e32 v125, v125, v126
	v_add_f32_e32 v124, v124, v125
	v_add_f32_e32 v0, v0, v124
	v_mbcnt_lo_u32_b32 v124, -1, 0
	v_mbcnt_hi_u32_b32 v124, -1, v124
	s_nop 0
	v_lshlrev_b32_e32 v124, 2, v124
	v_xor_b32_e32 v125, 64, v124
	ds_bpermute_b32 v125, v125, v0
	v_xor_b32_e32 v124, 0x80, v124
	s_waitcnt lgkmcnt(0)
	v_add_f32_e32 v0, v0, v125
	ds_bpermute_b32 v124, v124, v0
	s_and_saveexec_b64 s[24:25], s[6:7]
	s_cbranch_execz .LBB0_391
	s_waitcnt lgkmcnt(0)
	v_add_f32_e32 v124, v0, v124
	v_cvt_i32_f32_e32 v0, v124
	v_cvt_f32_i32_e32 v125, v0
	v_lshlrev_b64 v[126:127], 24, v[0:1]
	v_sub_f32_e32 v124, v124, v125
	v_mul_f32_e32 v124, 0x4b800000, v124
	v_cvt_i32_f32_e32 v124, v124
	v_mov_b32_e32 v125, v1
	v_lshl_add_u64 v[124:125], v[126:127], 0, v[124:125]
	global_atomic_add_x2 v[148:149], v[124:125], off offset:128
.LBB0_391:
	s_or_b64 exec, exec, s[24:25]
	s_waitcnt vmcnt(12)
	s_waitcnt lgkmcnt(0)
	v_or_b32_e32 v124, 32, v196
	v_cvt_f32_f16_e32 v128, v192
	v_cvt_f32_f16_sdwa v129, v192 dst_sel:DWORD dst_unused:UNUSED_PAD src0_sel:WORD_1
	v_cvt_f32_f16_e32 v126, v193
	v_cvt_f32_f16_sdwa v127, v193 dst_sel:DWORD dst_unused:UNUSED_PAD src0_sel:WORD_1
	v_ashrrev_i32_e32 v125, 31, v124
	v_pk_fma_f32 v[108:109], v[108:109], s[10:11], v[128:129]
	v_cvt_f32_f16_e32 v128, v194
	v_cvt_f32_f16_sdwa v129, v194 dst_sel:DWORD dst_unused:UNUSED_PAD src0_sel:WORD_1
	v_pk_fma_f32 v[110:111], v[110:111], s[22:23], v[126:127]
	v_cvt_f32_f16_e32 v126, v195
	v_cvt_f32_f16_sdwa v127, v195 dst_sel:DWORD dst_unused:UNUSED_PAD src0_sel:WORD_1
	v_pk_fma_f32 v[128:129], v[100:101], s[10:11], v[128:129]
	v_cvt_pk_f16_f32 v101, v110, v111
	v_cvt_pk_f16_f32 v100, v108, v109
	v_pk_fma_f32 v[102:103], v[102:103], s[22:23], v[126:127]
	v_cvt_f32_f16_sdwa v0, v101 dst_sel:DWORD dst_unused:UNUSED_PAD src0_sel:WORD_1
	v_cvt_f32_f16_sdwa v108, v100 dst_sel:DWORD dst_unused:UNUSED_PAD src0_sel:WORD_1
	v_cvt_pk_f16_f32 v103, v102, v103
	v_cvt_pk_f16_f32 v102, v128, v129
	v_cvt_f32_f16_sdwa v109, v103 dst_sel:DWORD dst_unused:UNUSED_PAD src0_sel:WORD_1
	v_cvt_f32_f16_sdwa v110, v102 dst_sel:DWORD dst_unused:UNUSED_PAD src0_sel:WORD_1
	v_lshlrev_b64 v[124:125], 12, v[124:125]
	v_lshl_add_u64 v[124:125], v[198:199], 0, v[124:125]
	v_mul_f32_e32 v108, v108, v108
	v_mul_f32_e32 v0, v0, v0
	global_store_dwordx4 v[124:125], v[100:103], off
	v_fma_mix_f32 v0, v101, v101, v0 op_sel_hi:[1,1,0]
	v_cvt_f32_f16_sdwa v111, v190 dst_sel:DWORD dst_unused:UNUSED_PAD src0_sel:WORD_1
	v_fma_mix_f32 v100, v100, v100, v108 op_sel_hi:[1,1,0]
	v_mul_f32_e32 v101, v109, v109
	v_add_f32_e32 v0, v100, v0
	v_mul_f32_e32 v100, v110, v110
	v_fma_mix_f32 v100, v102, v102, v100 op_sel_hi:[1,1,0]
	v_fma_mix_f32 v101, v103, v103, v101 op_sel_hi:[1,1,0]
	v_cvt_f32_f16_e32 v102, v188
	v_add_f32_e32 v100, v100, v101
	v_add_f32_e32 v0, v0, v100
	v_cvt_f32_f16_e32 v100, v189
	v_cvt_f32_f16_sdwa v101, v189 dst_sel:DWORD dst_unused:UNUSED_PAD src0_sel:WORD_1
	v_cvt_f32_f16_sdwa v103, v188 dst_sel:DWORD dst_unused:UNUSED_PAD src0_sel:WORD_1
	v_cvt_f32_f16_e32 v110, v190
	v_cvt_f32_f16_e32 v108, v191
	v_cvt_f32_f16_sdwa v109, v191 dst_sel:DWORD dst_unused:UNUSED_PAD src0_sel:WORD_1
	v_pk_fma_f32 v[102:103], v[112:113], s[10:11], v[102:103]
	v_pk_fma_f32 v[100:101], v[114:115], s[22:23], v[100:101]
	v_pk_fma_f32 v[104:105], v[104:105], s[10:11], v[110:111]
	v_cvt_pk_f16_f32 v101, v100, v101
	v_cvt_pk_f16_f32 v100, v102, v103
	v_cvt_pk_f16_f32 v102, v104, v105
	v_cvt_f32_f16_sdwa v104, v101 dst_sel:DWORD dst_unused:UNUSED_PAD src0_sel:WORD_1
	v_cvt_f32_f16_sdwa v105, v100 dst_sel:DWORD dst_unused:UNUSED_PAD src0_sel:WORD_1
	v_pk_fma_f32 v[106:107], v[106:107], s[22:23], v[108:109]
	v_mul_f32_e32 v104, v104, v104
	v_cvt_pk_f16_f32 v103, v106, v107
	v_cvt_f32_f16_sdwa v107, v102 dst_sel:DWORD dst_unused:UNUSED_PAD src0_sel:WORD_1
	v_cvt_f32_f16_sdwa v106, v103 dst_sel:DWORD dst_unused:UNUSED_PAD src0_sel:WORD_1
	v_mul_f32_e32 v105, v105, v105
	global_store_dwordx4 v[124:125], v[100:103], off offset:256
	s_nop 1
	v_fma_mix_f32 v100, v100, v100, v105 op_sel_hi:[1,1,0]
	v_fma_mix_f32 v101, v101, v101, v104 op_sel_hi:[1,1,0]
	s_nop 0
	v_add_f32_e32 v100, v100, v101
	v_mul_f32_e32 v101, v107, v107
	v_fma_mix_f32 v101, v102, v102, v101 op_sel_hi:[1,1,0]
	v_mul_f32_e32 v102, v106, v106
	v_fma_mix_f32 v102, v103, v103, v102 op_sel_hi:[1,1,0]
	s_nop 0
	v_add_f32_e32 v101, v101, v102
	v_add_f32_e32 v100, v100, v101
	v_add_f32_e32 v0, v0, v100
	v_mbcnt_lo_u32_b32 v100, -1, 0
	v_mbcnt_hi_u32_b32 v100, -1, v100
	v_mov_b64_e32 v[102:103], 0
	v_lshlrev_b32_e32 v100, 2, v100
	v_xor_b32_e32 v101, 64, v100
	ds_bpermute_b32 v101, v101, v0
	v_xor_b32_e32 v100, 0x80, v100
	s_waitcnt lgkmcnt(0)
	v_add_f32_e32 v0, v0, v101
	ds_bpermute_b32 v104, v100, v0
	v_mov_b64_e32 v[100:101], 0
	s_and_saveexec_b64 s[22:23], s[6:7]
	s_cbranch_execz .LBB0_393
	s_waitcnt lgkmcnt(0)
	v_add_f32_e32 v102, v0, v104
	v_cvt_i32_f32_e32 v0, v102
	v_cvt_f32_i32_e32 v103, v0
	v_lshlrev_b64 v[104:105], 24, v[0:1]
	v_sub_f32_e32 v102, v102, v103
	v_mul_f32_e32 v102, 0x4b800000, v102
	v_cvt_i32_f32_e32 v102, v102
	v_mov_b32_e32 v103, v1
	v_lshl_add_u64 v[102:103], v[104:105], 0, v[102:103]
	global_atomic_add_x2 v[148:149], v[102:103], off offset:256
.LBB0_393:
	s_or_b64 exec, exec, s[22:23]
	v_cvt_f32_f16_sdwa v107, v184 dst_sel:DWORD dst_unused:UNUSED_PAD src0_sel:WORD_1
	v_cvt_f32_f16_e32 v106, v184
	v_cvt_f32_f16_sdwa v109, v185 dst_sel:DWORD dst_unused:UNUSED_PAD src0_sel:WORD_1
	v_cvt_f32_f16_e32 v108, v185
	s_mov_b32 s22, s10
	s_mov_b32 s23, s10
	v_pk_fma_f32 v[92:93], v[92:93], s[10:11], v[106:107]
	v_cvt_f32_f16_sdwa v107, v186 dst_sel:DWORD dst_unused:UNUSED_PAD src0_sel:WORD_1
	v_cvt_f32_f16_e32 v106, v186
	v_pk_fma_f32 v[94:95], v[94:95], s[22:23], v[108:109]
	v_cvt_f32_f16_sdwa v109, v187 dst_sel:DWORD dst_unused:UNUSED_PAD src0_sel:WORD_1
	v_cvt_f32_f16_e32 v108, v187
	v_pk_fma_f32 v[106:107], v[84:85], s[10:11], v[106:107]
	v_cvt_pk_f16_f32 v85, v94, v95
	v_cvt_pk_f16_f32 v84, v92, v93
	v_pk_fma_f32 v[86:87], v[86:87], s[22:23], v[108:109]
	v_cvt_f32_f16_sdwa v0, v85 dst_sel:DWORD dst_unused:UNUSED_PAD src0_sel:WORD_1
	v_cvt_f32_f16_sdwa v92, v84 dst_sel:DWORD dst_unused:UNUSED_PAD src0_sel:WORD_1
	s_waitcnt lgkmcnt(0)
	v_or_b32_e32 v104, 48, v196
	v_cvt_pk_f16_f32 v87, v86, v87
	v_cvt_pk_f16_f32 v86, v106, v107
	v_ashrrev_i32_e32 v105, 31, v104
	v_cvt_f32_f16_sdwa v93, v87 dst_sel:DWORD dst_unused:UNUSED_PAD src0_sel:WORD_1
	v_cvt_f32_f16_sdwa v94, v86 dst_sel:DWORD dst_unused:UNUSED_PAD src0_sel:WORD_1
	v_lshlrev_b64 v[104:105], 12, v[104:105]
	v_lshl_add_u64 v[104:105], v[198:199], 0, v[104:105]
	v_mul_f32_e32 v92, v92, v92
	v_mul_f32_e32 v0, v0, v0
	global_store_dwordx4 v[104:105], v[84:87], off
	v_fma_mix_f32 v0, v85, v85, v0 op_sel_hi:[1,1,0]
	v_cvt_f32_f16_sdwa v95, v183 dst_sel:DWORD dst_unused:UNUSED_PAD src0_sel:WORD_1
	v_fma_mix_f32 v84, v84, v84, v92 op_sel_hi:[1,1,0]
	v_mul_f32_e32 v85, v93, v93
	v_add_f32_e32 v0, v84, v0
	v_mul_f32_e32 v84, v94, v94
	v_fma_mix_f32 v84, v86, v86, v84 op_sel_hi:[1,1,0]
	v_fma_mix_f32 v85, v87, v87, v85 op_sel_hi:[1,1,0]
	v_cvt_f32_f16_sdwa v87, v181 dst_sel:DWORD dst_unused:UNUSED_PAD src0_sel:WORD_1
	v_add_f32_e32 v84, v84, v85
	v_add_f32_e32 v0, v0, v84
	v_cvt_f32_f16_sdwa v85, v180 dst_sel:DWORD dst_unused:UNUSED_PAD src0_sel:WORD_1
	v_cvt_f32_f16_e32 v84, v180
	v_cvt_f32_f16_e32 v86, v181
	v_cvt_f32_f16_e32 v94, v183
	v_pk_fma_f32 v[92:93], v[96:97], s[10:11], v[84:85]
	v_cvt_f32_f16_sdwa v85, v182 dst_sel:DWORD dst_unused:UNUSED_PAD src0_sel:WORD_1
	v_cvt_f32_f16_e32 v84, v182
	v_pk_fma_f32 v[86:87], v[98:99], s[22:23], v[86:87]
	v_pk_fma_f32 v[90:91], v[90:91], s[22:23], v[94:95]
	v_pk_fma_f32 v[88:89], v[88:89], s[10:11], v[84:85]
	v_cvt_pk_f16_f32 v85, v86, v87
	v_cvt_pk_f16_f32 v84, v92, v93
	v_cvt_pk_f16_f32 v86, v88, v89
	v_cvt_f32_f16_sdwa v88, v85 dst_sel:DWORD dst_unused:UNUSED_PAD src0_sel:WORD_1
	v_cvt_f32_f16_sdwa v89, v84 dst_sel:DWORD dst_unused:UNUSED_PAD src0_sel:WORD_1
	v_cvt_pk_f16_f32 v87, v90, v91
	v_cvt_f32_f16_sdwa v91, v86 dst_sel:DWORD dst_unused:UNUSED_PAD src0_sel:WORD_1
	v_cvt_f32_f16_sdwa v90, v87 dst_sel:DWORD dst_unused:UNUSED_PAD src0_sel:WORD_1
	v_mul_f32_e32 v89, v89, v89
	v_mul_f32_e32 v88, v88, v88
	global_store_dwordx4 v[104:105], v[84:87], off offset:256
	s_nop 1
	v_fma_mix_f32 v84, v84, v84, v89 op_sel_hi:[1,1,0]
	v_fma_mix_f32 v85, v85, v85, v88 op_sel_hi:[1,1,0]
	s_nop 0
	v_add_f32_e32 v84, v84, v85
	v_mul_f32_e32 v85, v91, v91
	v_fma_mix_f32 v85, v86, v86, v85 op_sel_hi:[1,1,0]
	v_mul_f32_e32 v86, v90, v90
	v_fma_mix_f32 v86, v87, v87, v86 op_sel_hi:[1,1,0]
	s_nop 0
	v_add_f32_e32 v85, v85, v86
	v_add_f32_e32 v84, v84, v85
	v_add_f32_e32 v0, v0, v84
	v_mbcnt_lo_u32_b32 v84, -1, 0
	v_mbcnt_hi_u32_b32 v84, -1, v84
	s_nop 0
	v_lshlrev_b32_e32 v84, 2, v84
	v_xor_b32_e32 v85, 64, v84
	ds_bpermute_b32 v85, v85, v0
	v_xor_b32_e32 v84, 0x80, v84
	s_waitcnt lgkmcnt(0)
	v_add_f32_e32 v0, v0, v85
	ds_bpermute_b32 v84, v84, v0
	s_and_saveexec_b64 s[24:25], s[6:7]
	s_cbranch_execz .LBB0_395
	s_waitcnt lgkmcnt(0)
	v_add_f32_e32 v84, v0, v84
	v_cvt_i32_f32_e32 v0, v84
	v_cvt_f32_i32_e32 v85, v0
	v_lshlrev_b64 v[86:87], 24, v[0:1]
	v_sub_f32_e32 v84, v84, v85
	v_mul_f32_e32 v84, 0x4b800000, v84
	v_cvt_i32_f32_e32 v84, v84
	v_mov_b32_e32 v85, v1
	v_lshl_add_u64 v[84:85], v[86:87], 0, v[84:85]
	global_atomic_add_x2 v[148:149], v[84:85], off offset:384
.LBB0_395:
	s_or_b64 exec, exec, s[24:25]
	s_waitcnt vmcnt(12)
	s_mov_b64 s[24:25], 0x80000
	v_cvt_f32_f16_e32 v86, v177
	v_cvt_f32_f16_sdwa v87, v177 dst_sel:DWORD dst_unused:UNUSED_PAD src0_sel:WORD_1
	v_cvt_f32_f16_e32 v88, v176
	v_cvt_f32_f16_sdwa v89, v176 dst_sel:DWORD dst_unused:UNUSED_PAD src0_sel:WORD_1
	s_waitcnt lgkmcnt(0)
	v_lshl_add_u64 v[84:85], v[2:3], 0, s[24:25]
	v_pk_fma_f32 v[78:79], v[78:79], s[22:23], v[86:87]
	v_cvt_f32_f16_e32 v86, v179
	v_pk_fma_f32 v[76:77], v[76:77], s[10:11], v[88:89]
	v_cvt_f32_f16_sdwa v87, v179 dst_sel:DWORD dst_unused:UNUSED_PAD src0_sel:WORD_1
	v_cvt_f32_f16_e32 v88, v178
	v_cvt_f32_f16_sdwa v89, v178 dst_sel:DWORD dst_unused:UNUSED_PAD src0_sel:WORD_1
	v_pk_fma_f32 v[70:71], v[70:71], s[22:23], v[86:87]
	s_nop 0
	v_cvt_pk_f16_f32 v71, v70, v71
	v_pk_fma_f32 v[88:89], v[68:69], s[10:11], v[88:89]
	v_cvt_pk_f16_f32 v68, v76, v77
	v_add_co_u32_e32 v76, vcc, s70, v2
	v_cvt_pk_f16_f32 v69, v78, v79
	v_cvt_pk_f16_f32 v70, v88, v89
	v_addc_co_u32_e32 v77, vcc, 0, v3, vcc
	global_store_dwordx4 v[76:77], v[68:71], off
	v_cvt_f32_f16_sdwa v0, v69 dst_sel:DWORD dst_unused:UNUSED_PAD src0_sel:WORD_1
	v_cvt_f32_f16_sdwa v76, v68 dst_sel:DWORD dst_unused:UNUSED_PAD src0_sel:WORD_1
	v_cvt_f32_f16_sdwa v77, v71 dst_sel:DWORD dst_unused:UNUSED_PAD src0_sel:WORD_1
	v_cvt_f32_f16_sdwa v78, v70 dst_sel:DWORD dst_unused:UNUSED_PAD src0_sel:WORD_1
	v_mul_f32_e32 v0, v0, v0
	v_mul_f32_e32 v76, v76, v76
	v_fma_mix_f32 v68, v68, v68, v76 op_sel_hi:[1,1,0]
	v_fma_mix_f32 v0, v69, v69, v0 op_sel_hi:[1,1,0]
	v_mul_f32_e32 v69, v77, v77
	v_add_f32_e32 v0, v68, v0
	v_mul_f32_e32 v68, v78, v78
	v_fma_mix_f32 v68, v70, v70, v68 op_sel_hi:[1,1,0]
	v_fma_mix_f32 v69, v71, v71, v69 op_sel_hi:[1,1,0]
	v_cvt_f32_f16_e32 v70, v172
	v_add_f32_e32 v68, v68, v69
	v_add_f32_e32 v0, v0, v68
	v_cvt_f32_f16_e32 v68, v173
	v_cvt_f32_f16_sdwa v69, v173 dst_sel:DWORD dst_unused:UNUSED_PAD src0_sel:WORD_1
	v_cvt_f32_f16_sdwa v71, v172 dst_sel:DWORD dst_unused:UNUSED_PAD src0_sel:WORD_1
	v_cvt_f32_f16_e32 v78, v174
	v_cvt_f32_f16_sdwa v79, v174 dst_sel:DWORD dst_unused:UNUSED_PAD src0_sel:WORD_1
	v_cvt_f32_f16_e32 v76, v175
	v_cvt_f32_f16_sdwa v77, v175 dst_sel:DWORD dst_unused:UNUSED_PAD src0_sel:WORD_1
	v_pk_fma_f32 v[70:71], v[80:81], s[10:11], v[70:71]
	v_pk_fma_f32 v[68:69], v[82:83], s[22:23], v[68:69]
	v_pk_fma_f32 v[72:73], v[72:73], s[10:11], v[78:79]
	v_cvt_pk_f16_f32 v69, v68, v69
	v_cvt_pk_f16_f32 v68, v70, v71
	v_cvt_pk_f16_f32 v70, v72, v73
	v_cvt_f32_f16_sdwa v72, v69 dst_sel:DWORD dst_unused:UNUSED_PAD src0_sel:WORD_1
	v_cvt_f32_f16_sdwa v73, v68 dst_sel:DWORD dst_unused:UNUSED_PAD src0_sel:WORD_1
	v_pk_fma_f32 v[74:75], v[74:75], s[22:23], v[76:77]
	v_mul_f32_e32 v72, v72, v72
	v_cvt_pk_f16_f32 v71, v74, v75
	v_cvt_f32_f16_sdwa v75, v70 dst_sel:DWORD dst_unused:UNUSED_PAD src0_sel:WORD_1
	v_cvt_f32_f16_sdwa v74, v71 dst_sel:DWORD dst_unused:UNUSED_PAD src0_sel:WORD_1
	v_mul_f32_e32 v73, v73, v73
	global_store_dwordx4 v[84:85], v[68:71], off offset:256
	s_nop 1
	v_fma_mix_f32 v68, v68, v68, v73 op_sel_hi:[1,1,0]
	v_fma_mix_f32 v69, v69, v69, v72 op_sel_hi:[1,1,0]
	s_nop 0
	v_add_f32_e32 v68, v68, v69
	v_mul_f32_e32 v69, v75, v75
	v_fma_mix_f32 v69, v70, v70, v69 op_sel_hi:[1,1,0]
	v_mul_f32_e32 v70, v74, v74
	v_fma_mix_f32 v70, v71, v71, v70 op_sel_hi:[1,1,0]
	s_nop 0
	v_add_f32_e32 v69, v69, v70
	v_add_f32_e32 v68, v68, v69
	v_add_f32_e32 v0, v0, v68
	v_mbcnt_lo_u32_b32 v68, -1, 0
	v_mbcnt_hi_u32_b32 v68, -1, v68
	v_mov_b64_e32 v[70:71], 0
	v_lshlrev_b32_e32 v68, 2, v68
	v_xor_b32_e32 v69, 64, v68
	ds_bpermute_b32 v69, v69, v0
	v_xor_b32_e32 v68, 0x80, v68
	s_waitcnt lgkmcnt(0)
	v_add_f32_e32 v0, v0, v69
	ds_bpermute_b32 v72, v68, v0
	v_mov_b64_e32 v[68:69], 0
	s_and_saveexec_b64 s[22:23], s[6:7]
	s_cbranch_execz .LBB0_397
	s_waitcnt lgkmcnt(0)
	v_add_f32_e32 v70, v0, v72
	v_cvt_i32_f32_e32 v0, v70
	v_cvt_f32_i32_e32 v71, v0
	v_lshlrev_b64 v[72:73], 24, v[0:1]
	v_sub_f32_e32 v70, v70, v71
	v_mul_f32_e32 v70, 0x4b800000, v70
	v_cvt_i32_f32_e32 v70, v70
	v_mov_b32_e32 v71, v1
	v_lshl_add_u64 v[70:71], v[72:73], 0, v[70:71]
	global_atomic_add_x2 v[148:149], v[70:71], off offset:1024
.LBB0_397:
	s_or_b64 exec, exec, s[22:23]
	v_cvt_f32_f16_sdwa v75, v168 dst_sel:DWORD dst_unused:UNUSED_PAD src0_sel:WORD_1
	v_cvt_f32_f16_sdwa v77, v169 dst_sel:DWORD dst_unused:UNUSED_PAD src0_sel:WORD_1
	v_cvt_f32_f16_e32 v74, v168
	v_cvt_f32_f16_e32 v76, v169
	s_mov_b64 s[22:23], 0x90000
	s_waitcnt lgkmcnt(0)
	v_lshl_add_u64 v[72:73], v[2:3], 0, s[22:23]
	s_mov_b32 s22, s10
	s_mov_b32 s23, s10
	v_pk_fma_f32 v[62:63], v[62:63], s[22:23], v[76:77]
	v_pk_fma_f32 v[60:61], v[60:61], s[10:11], v[74:75]
	v_cvt_f32_f16_sdwa v75, v170 dst_sel:DWORD dst_unused:UNUSED_PAD src0_sel:WORD_1
	v_cvt_f32_f16_sdwa v77, v171 dst_sel:DWORD dst_unused:UNUSED_PAD src0_sel:WORD_1
	v_cvt_f32_f16_e32 v74, v170
	v_cvt_f32_f16_e32 v76, v171
	s_mov_b32 s24, 0x90000
	v_pk_fma_f32 v[74:75], v[52:53], s[10:11], v[74:75]
	v_pk_fma_f32 v[54:55], v[54:55], s[22:23], v[76:77]
	v_cvt_pk_f16_f32 v52, v60, v61
	v_add_co_u32_e32 v60, vcc, s24, v2
	v_cvt_pk_f16_f32 v53, v62, v63
	v_cvt_pk_f16_f32 v55, v54, v55
	v_cvt_pk_f16_f32 v54, v74, v75
	v_addc_co_u32_e32 v61, vcc, 0, v3, vcc
	global_store_dwordx4 v[60:61], v[52:55], off
	v_cvt_f32_f16_sdwa v0, v53 dst_sel:DWORD dst_unused:UNUSED_PAD src0_sel:WORD_1
	v_cvt_f32_f16_sdwa v60, v52 dst_sel:DWORD dst_unused:UNUSED_PAD src0_sel:WORD_1
	v_cvt_f32_f16_sdwa v61, v55 dst_sel:DWORD dst_unused:UNUSED_PAD src0_sel:WORD_1
	v_cvt_f32_f16_sdwa v62, v54 dst_sel:DWORD dst_unused:UNUSED_PAD src0_sel:WORD_1
	v_mul_f32_e32 v0, v0, v0
	v_mul_f32_e32 v60, v60, v60
	v_fma_mix_f32 v52, v52, v52, v60 op_sel_hi:[1,1,0]
	v_fma_mix_f32 v0, v53, v53, v0 op_sel_hi:[1,1,0]
	v_mul_f32_e32 v53, v61, v61
	v_add_f32_e32 v0, v52, v0
	v_mul_f32_e32 v52, v62, v62
	v_fma_mix_f32 v52, v54, v54, v52 op_sel_hi:[1,1,0]
	v_fma_mix_f32 v53, v55, v55, v53 op_sel_hi:[1,1,0]
	v_cvt_f32_f16_sdwa v55, v165 dst_sel:DWORD dst_unused:UNUSED_PAD src0_sel:WORD_1
	v_add_f32_e32 v52, v52, v53
	v_add_f32_e32 v0, v0, v52
	v_cvt_f32_f16_sdwa v53, v164 dst_sel:DWORD dst_unused:UNUSED_PAD src0_sel:WORD_1
	v_cvt_f32_f16_e32 v52, v164
	v_cvt_f32_f16_e32 v54, v165
	v_cvt_f32_f16_sdwa v63, v167 dst_sel:DWORD dst_unused:UNUSED_PAD src0_sel:WORD_1
	v_cvt_f32_f16_e32 v62, v167
	v_pk_fma_f32 v[60:61], v[64:65], s[10:11], v[52:53]
	v_cvt_f32_f16_sdwa v53, v166 dst_sel:DWORD dst_unused:UNUSED_PAD src0_sel:WORD_1
	v_cvt_f32_f16_e32 v52, v166
	v_pk_fma_f32 v[54:55], v[66:67], s[22:23], v[54:55]
	v_pk_fma_f32 v[58:59], v[58:59], s[22:23], v[62:63]
	v_pk_fma_f32 v[56:57], v[56:57], s[10:11], v[52:53]
	v_cvt_pk_f16_f32 v53, v54, v55
	v_cvt_pk_f16_f32 v52, v60, v61
	v_cvt_pk_f16_f32 v54, v56, v57
	v_cvt_f32_f16_sdwa v56, v53 dst_sel:DWORD dst_unused:UNUSED_PAD src0_sel:WORD_1
	v_cvt_f32_f16_sdwa v57, v52 dst_sel:DWORD dst_unused:UNUSED_PAD src0_sel:WORD_1
	v_cvt_pk_f16_f32 v55, v58, v59
	v_cvt_f32_f16_sdwa v59, v54 dst_sel:DWORD dst_unused:UNUSED_PAD src0_sel:WORD_1
	v_cvt_f32_f16_sdwa v58, v55 dst_sel:DWORD dst_unused:UNUSED_PAD src0_sel:WORD_1
	v_mul_f32_e32 v57, v57, v57
	v_mul_f32_e32 v56, v56, v56
	global_store_dwordx4 v[72:73], v[52:55], off offset:256
	s_nop 1
	v_fma_mix_f32 v52, v52, v52, v57 op_sel_hi:[1,1,0]
	v_fma_mix_f32 v53, v53, v53, v56 op_sel_hi:[1,1,0]
	s_nop 0
	v_add_f32_e32 v52, v52, v53
	v_mul_f32_e32 v53, v59, v59
	v_fma_mix_f32 v53, v54, v54, v53 op_sel_hi:[1,1,0]
	v_mul_f32_e32 v54, v58, v58
	v_fma_mix_f32 v54, v55, v55, v54 op_sel_hi:[1,1,0]
	s_nop 0
	v_add_f32_e32 v53, v53, v54
	v_add_f32_e32 v52, v52, v53
	v_add_f32_e32 v0, v0, v52
	v_mbcnt_lo_u32_b32 v52, -1, 0
	v_mbcnt_hi_u32_b32 v52, -1, v52
	s_nop 0
	v_lshlrev_b32_e32 v52, 2, v52
	v_xor_b32_e32 v53, 64, v52
	ds_bpermute_b32 v53, v53, v0
	v_xor_b32_e32 v52, 0x80, v52
	s_waitcnt lgkmcnt(0)
	v_add_f32_e32 v0, v0, v53
	ds_bpermute_b32 v52, v52, v0
	s_and_saveexec_b64 s[24:25], s[6:7]
	s_cbranch_execz .LBB0_399
	s_waitcnt lgkmcnt(0)
	v_add_f32_e32 v52, v0, v52
	v_cvt_i32_f32_e32 v0, v52
	v_cvt_f32_i32_e32 v53, v0
	v_lshlrev_b64 v[54:55], 24, v[0:1]
	v_sub_f32_e32 v52, v52, v53
	v_mul_f32_e32 v52, 0x4b800000, v52
	v_cvt_i32_f32_e32 v52, v52
	v_mov_b32_e32 v53, v1
	v_lshl_add_u64 v[52:53], v[54:55], 0, v[52:53]
	global_atomic_add_x2 v[148:149], v[52:53], off offset:1152
.LBB0_399:
	s_or_b64 exec, exec, s[24:25]
	s_waitcnt vmcnt(12)
	s_mov_b64 s[24:25], 0xa0000
	v_cvt_f32_f16_e32 v54, v145
	v_cvt_f32_f16_sdwa v55, v145 dst_sel:DWORD dst_unused:UNUSED_PAD src0_sel:WORD_1
	v_cvt_f32_f16_e32 v56, v144
	v_cvt_f32_f16_sdwa v57, v144 dst_sel:DWORD dst_unused:UNUSED_PAD src0_sel:WORD_1
	s_waitcnt lgkmcnt(0)
	v_lshl_add_u64 v[52:53], v[2:3], 0, s[24:25]
	v_pk_fma_f32 v[46:47], v[46:47], s[22:23], v[54:55]
	v_cvt_f32_f16_e32 v54, v147
	v_pk_fma_f32 v[44:45], v[44:45], s[10:11], v[56:57]
	v_cvt_f32_f16_sdwa v55, v147 dst_sel:DWORD dst_unused:UNUSED_PAD src0_sel:WORD_1
	v_cvt_f32_f16_e32 v56, v146
	v_cvt_f32_f16_sdwa v57, v146 dst_sel:DWORD dst_unused:UNUSED_PAD src0_sel:WORD_1
	s_mov_b32 s24, 0xa0000
	v_pk_fma_f32 v[38:39], v[38:39], s[22:23], v[54:55]
	v_pk_fma_f32 v[56:57], v[36:37], s[10:11], v[56:57]
	v_cvt_pk_f16_f32 v36, v44, v45
	v_add_co_u32_e32 v44, vcc, s24, v2
	v_cvt_pk_f16_f32 v37, v46, v47
	v_cvt_pk_f16_f32 v39, v38, v39
	v_cvt_pk_f16_f32 v38, v56, v57
	v_addc_co_u32_e32 v45, vcc, 0, v3, vcc
	global_store_dwordx4 v[44:45], v[36:39], off
	v_cvt_f32_f16_sdwa v0, v37 dst_sel:DWORD dst_unused:UNUSED_PAD src0_sel:WORD_1
	v_cvt_f32_f16_sdwa v44, v36 dst_sel:DWORD dst_unused:UNUSED_PAD src0_sel:WORD_1
	v_cvt_f32_f16_sdwa v45, v39 dst_sel:DWORD dst_unused:UNUSED_PAD src0_sel:WORD_1
	v_cvt_f32_f16_sdwa v46, v38 dst_sel:DWORD dst_unused:UNUSED_PAD src0_sel:WORD_1
	v_mul_f32_e32 v0, v0, v0
	v_mul_f32_e32 v44, v44, v44
	v_fma_mix_f32 v36, v36, v36, v44 op_sel_hi:[1,1,0]
	v_fma_mix_f32 v0, v37, v37, v0 op_sel_hi:[1,1,0]
	v_mul_f32_e32 v37, v45, v45
	v_add_f32_e32 v0, v36, v0
	v_mul_f32_e32 v36, v46, v46
	v_fma_mix_f32 v36, v38, v38, v36 op_sel_hi:[1,1,0]
	v_fma_mix_f32 v37, v39, v39, v37 op_sel_hi:[1,1,0]
	v_cvt_f32_f16_e32 v38, v140
	v_add_f32_e32 v36, v36, v37
	v_add_f32_e32 v0, v0, v36
	v_cvt_f32_f16_e32 v36, v141
	v_cvt_f32_f16_sdwa v37, v141 dst_sel:DWORD dst_unused:UNUSED_PAD src0_sel:WORD_1
	v_cvt_f32_f16_sdwa v39, v140 dst_sel:DWORD dst_unused:UNUSED_PAD src0_sel:WORD_1
	v_cvt_f32_f16_e32 v46, v142
	v_cvt_f32_f16_sdwa v47, v142 dst_sel:DWORD dst_unused:UNUSED_PAD src0_sel:WORD_1
	v_cvt_f32_f16_e32 v44, v143
	v_cvt_f32_f16_sdwa v45, v143 dst_sel:DWORD dst_unused:UNUSED_PAD src0_sel:WORD_1
	v_pk_fma_f32 v[38:39], v[48:49], s[10:11], v[38:39]
	v_pk_fma_f32 v[36:37], v[50:51], s[22:23], v[36:37]
	v_pk_fma_f32 v[40:41], v[40:41], s[10:11], v[46:47]
	v_cvt_pk_f16_f32 v37, v36, v37
	v_cvt_pk_f16_f32 v36, v38, v39
	v_cvt_pk_f16_f32 v38, v40, v41
	v_cvt_f32_f16_sdwa v40, v37 dst_sel:DWORD dst_unused:UNUSED_PAD src0_sel:WORD_1
	v_cvt_f32_f16_sdwa v41, v36 dst_sel:DWORD dst_unused:UNUSED_PAD src0_sel:WORD_1
	v_pk_fma_f32 v[42:43], v[42:43], s[22:23], v[44:45]
	v_mul_f32_e32 v40, v40, v40
	v_cvt_pk_f16_f32 v39, v42, v43
	v_cvt_f32_f16_sdwa v43, v38 dst_sel:DWORD dst_unused:UNUSED_PAD src0_sel:WORD_1
	v_cvt_f32_f16_sdwa v42, v39 dst_sel:DWORD dst_unused:UNUSED_PAD src0_sel:WORD_1
	v_mul_f32_e32 v41, v41, v41
	global_store_dwordx4 v[52:53], v[36:39], off offset:256
	s_nop 1
	v_fma_mix_f32 v36, v36, v36, v41 op_sel_hi:[1,1,0]
	v_fma_mix_f32 v37, v37, v37, v40 op_sel_hi:[1,1,0]
	s_nop 0
	v_add_f32_e32 v36, v36, v37
	v_mul_f32_e32 v37, v43, v43
	v_fma_mix_f32 v37, v38, v38, v37 op_sel_hi:[1,1,0]
	v_mul_f32_e32 v38, v42, v42
	v_fma_mix_f32 v38, v39, v39, v38 op_sel_hi:[1,1,0]
	s_nop 0
	v_add_f32_e32 v37, v37, v38
	v_add_f32_e32 v36, v36, v37
	v_add_f32_e32 v0, v0, v36
	v_mbcnt_lo_u32_b32 v36, -1, 0
	v_mbcnt_hi_u32_b32 v36, -1, v36
	v_mov_b64_e32 v[38:39], 0
	v_lshlrev_b32_e32 v36, 2, v36
	v_xor_b32_e32 v37, 64, v36
	ds_bpermute_b32 v37, v37, v0
	v_xor_b32_e32 v36, 0x80, v36
	s_waitcnt lgkmcnt(0)
	v_add_f32_e32 v0, v0, v37
	ds_bpermute_b32 v40, v36, v0
	v_mov_b64_e32 v[36:37], 0
	s_and_saveexec_b64 s[22:23], s[6:7]
	s_cbranch_execz .LBB0_401
	s_waitcnt lgkmcnt(0)
	v_add_f32_e32 v38, v0, v40
	v_cvt_i32_f32_e32 v0, v38
	v_cvt_f32_i32_e32 v39, v0
	v_lshlrev_b64 v[40:41], 24, v[0:1]
	v_sub_f32_e32 v38, v38, v39
	v_mul_f32_e32 v38, 0x4b800000, v38
	v_cvt_i32_f32_e32 v38, v38
	v_mov_b32_e32 v39, v1
	v_lshl_add_u64 v[38:39], v[40:41], 0, v[38:39]
	global_atomic_add_x2 v[148:149], v[38:39], off offset:1280
.LBB0_401:
	s_or_b64 exec, exec, s[22:23]
	v_cvt_f32_f16_sdwa v43, v120 dst_sel:DWORD dst_unused:UNUSED_PAD src0_sel:WORD_1
	v_cvt_f32_f16_sdwa v45, v121 dst_sel:DWORD dst_unused:UNUSED_PAD src0_sel:WORD_1
	v_cvt_f32_f16_e32 v42, v120
	v_cvt_f32_f16_e32 v44, v121
	s_mov_b64 s[22:23], 0xb0000
	s_waitcnt lgkmcnt(0)
	v_lshl_add_u64 v[40:41], v[2:3], 0, s[22:23]
	s_mov_b32 s22, s10
	s_mov_b32 s23, s10
	v_pk_fma_f32 v[26:27], v[26:27], s[22:23], v[44:45]
	v_pk_fma_f32 v[24:25], v[24:25], s[10:11], v[42:43]
	v_cvt_f32_f16_sdwa v43, v122 dst_sel:DWORD dst_unused:UNUSED_PAD src0_sel:WORD_1
	v_cvt_f32_f16_sdwa v45, v123 dst_sel:DWORD dst_unused:UNUSED_PAD src0_sel:WORD_1
	v_cvt_f32_f16_e32 v42, v122
	v_cvt_f32_f16_e32 v44, v123
	s_mov_b32 s24, 0xb0000
	v_add_co_u32_e32 v2, vcc, s24, v2
	v_pk_fma_f32 v[22:23], v[22:23], s[22:23], v[44:45]
	v_pk_fma_f32 v[42:43], v[20:21], s[10:11], v[42:43]
	v_cvt_pk_f16_f32 v21, v26, v27
	v_cvt_pk_f16_f32 v20, v24, v25
	v_cvt_pk_f16_f32 v23, v22, v23
	v_cvt_pk_f16_f32 v22, v42, v43
	v_addc_co_u32_e32 v3, vcc, 0, v3, vcc
	global_store_dwordx4 v[2:3], v[20:23], off
	v_cvt_f32_f16_sdwa v0, v21 dst_sel:DWORD dst_unused:UNUSED_PAD src0_sel:WORD_1
	v_cvt_f32_f16_sdwa v2, v20 dst_sel:DWORD dst_unused:UNUSED_PAD src0_sel:WORD_1
	v_cvt_f32_f16_sdwa v3, v23 dst_sel:DWORD dst_unused:UNUSED_PAD src0_sel:WORD_1
	v_cvt_f32_f16_sdwa v24, v22 dst_sel:DWORD dst_unused:UNUSED_PAD src0_sel:WORD_1
	v_mul_f32_e32 v0, v0, v0
	v_mul_f32_e32 v2, v2, v2
	v_fma_mix_f32 v2, v20, v20, v2 op_sel_hi:[1,1,0]
	v_fma_mix_f32 v0, v21, v21, v0 op_sel_hi:[1,1,0]
	v_mul_f32_e32 v3, v3, v3
	v_add_f32_e32 v0, v2, v0
	v_mul_f32_e32 v2, v24, v24
	v_fma_mix_f32 v2, v22, v22, v2 op_sel_hi:[1,1,0]
	v_fma_mix_f32 v3, v23, v23, v3 op_sel_hi:[1,1,0]
	v_cvt_f32_f16_sdwa v21, v117 dst_sel:DWORD dst_unused:UNUSED_PAD src0_sel:WORD_1
	v_add_f32_e32 v2, v2, v3
	v_add_f32_e32 v0, v0, v2
	v_cvt_f32_f16_sdwa v3, v116 dst_sel:DWORD dst_unused:UNUSED_PAD src0_sel:WORD_1
	v_cvt_f32_f16_e32 v2, v116
	v_cvt_f32_f16_e32 v20, v117
	v_cvt_f32_f16_sdwa v23, v118 dst_sel:DWORD dst_unused:UNUSED_PAD src0_sel:WORD_1
	v_cvt_f32_f16_sdwa v25, v119 dst_sel:DWORD dst_unused:UNUSED_PAD src0_sel:WORD_1
	v_cvt_f32_f16_e32 v22, v118
	v_cvt_f32_f16_e32 v24, v119
	v_pk_fma_f32 v[20:21], v[30:31], s[22:23], v[20:21]
	v_pk_fma_f32 v[2:3], v[28:29], s[10:11], v[2:3]
	v_cvt_pk_f16_f32 v21, v20, v21
	v_cvt_pk_f16_f32 v20, v2, v3
	v_pk_fma_f32 v[24:25], v[34:35], s[22:23], v[24:25]
	v_pk_fma_f32 v[26:27], v[32:33], s[10:11], v[22:23]
	v_cvt_f32_f16_sdwa v2, v21 dst_sel:DWORD dst_unused:UNUSED_PAD src0_sel:WORD_1
	v_cvt_f32_f16_sdwa v3, v20 dst_sel:DWORD dst_unused:UNUSED_PAD src0_sel:WORD_1
	v_cvt_pk_f16_f32 v23, v24, v25
	v_cvt_pk_f16_f32 v22, v26, v27
	v_cvt_f32_f16_sdwa v24, v23 dst_sel:DWORD dst_unused:UNUSED_PAD src0_sel:WORD_1
	v_cvt_f32_f16_sdwa v25, v22 dst_sel:DWORD dst_unused:UNUSED_PAD src0_sel:WORD_1
	v_mul_f32_e32 v3, v3, v3
	v_mul_f32_e32 v2, v2, v2
	v_fma_mix_f32 v3, v20, v20, v3 op_sel_hi:[1,1,0]
	v_fma_mix_f32 v2, v21, v21, v2 op_sel_hi:[1,1,0]
	global_store_dwordx4 v[40:41], v[20:23], off offset:256
	v_add_f32_e32 v2, v3, v2
	v_mul_f32_e32 v3, v25, v25
	v_mul_f32_e32 v20, v24, v24
	v_fma_mix_f32 v3, v22, v22, v3 op_sel_hi:[1,1,0]
	v_fma_mix_f32 v20, v23, v23, v20 op_sel_hi:[1,1,0]
	s_nop 0
	v_add_f32_e32 v3, v3, v20
	v_add_f32_e32 v2, v2, v3
	v_add_f32_e32 v0, v0, v2
	v_mbcnt_lo_u32_b32 v2, -1, 0
	v_mbcnt_hi_u32_b32 v2, -1, v2
	s_nop 0
	v_lshlrev_b32_e32 v2, 2, v2
	v_xor_b32_e32 v3, 64, v2
	ds_bpermute_b32 v3, v3, v0
	v_xor_b32_e32 v2, 0x80, v2
	s_waitcnt lgkmcnt(0)
	v_add_f32_e32 v0, v0, v3
	ds_bpermute_b32 v2, v2, v0
	s_and_saveexec_b64 s[10:11], s[6:7]
	s_cbranch_execz .LBB0_403
	s_waitcnt lgkmcnt(0)
	v_add_f32_e32 v2, v0, v2
	v_cvt_i32_f32_e32 v0, v2
	v_cvt_f32_i32_e32 v3, v0
	v_lshlrev_b64 v[20:21], 24, v[0:1]
	v_sub_f32_e32 v2, v2, v3
	v_mul_f32_e32 v2, 0x4b800000, v2
	v_cvt_i32_f32_e32 v2, v2
	v_mov_b32_e32 v3, v1
	v_lshl_add_u64 v[2:3], v[20:21], 0, v[2:3]
	global_atomic_add_x2 v[148:149], v[2:3], off offset:1408
.LBB0_403:
	s_or_b64 exec, exec, s[10:11]
	s_andn2_b64 vcc, exec, s[4:5]
	s_mov_b64 s[4:5], -1
	s_cbranch_vccnz .LBB0_374
	s_waitcnt lgkmcnt(0)
	v_mov_b32_e32 v2, v1
	v_mov_b32_e32 v3, v1
	v_mov_b32_e32 v0, v1
	v_mov_b64_e32 v[34:35], v[2:3]
	v_mov_b64_e32 v[32:33], v[0:1]
	s_andn2_b64 vcc, exec, s[14:15]
	s_cbranch_vccnz .LBB0_373
	s_barrier
	s_branch .LBB0_373
